# v58 + attention: 78 packed s-minus-rowmax subtractions (v_pk_add_f32) split into scalar v_sub_f32 pairs, bit-identical, same byte size
# baseline (speedup 1.0000x reference)
.LBB0_1604:
	v_add_u32_e32 v0, s22, v244
	ds_read_b64_tr_b16 v[208:209], v0 offset:24576
	ds_read_b64_tr_b16 v[210:211], v0 offset:25088
	s_waitcnt lgkmcnt(9)
	v_mfma_f32_32x32x16_bf16 v[112:127], v[204:207], v[172:175], 0
	v_add_f32_e32 v2, v87, v88
	v_cvt_pk_bf16_f32 v156, v96, v97
	v_cvt_pk_bf16_f32 v157, v98, v99
	ds_read_b64_tr_b16 v[204:205], v0 offset:28672
	ds_read_b64_tr_b16 v[206:207], v0 offset:29184
	v_add_f32_e32 v2, v89, v2
	v_cvt_pk_bf16_f32 v158, v100, v101
	v_cvt_pk_bf16_f32 v159, v102, v103
	s_waitcnt lgkmcnt(10)
	v_mfma_f32_32x32x16_bf16 v[128:143], v[200:203], v[172:175], 0
	ds_read_b64_tr_b16 v[10:11], v0 offset:25600
	ds_read_b64_tr_b16 v[12:13], v0 offset:26112
	s_waitcnt lgkmcnt(11)
	v_mfma_f32_32x32x16_bf16 v[112:127], v[196:199], v[168:171], v[112:127]
	v_add_f32_e32 v2, v90, v2
	v_cvt_pk_bf16_f32 v152, v104, v105
	v_cvt_pk_bf16_f32 v153, v106, v107
	ds_read_b64_tr_b16 v[6:7], v0 offset:29696
	ds_read_b64_tr_b16 v[8:9], v0 offset:30208
	v_add_f32_e32 v14, v91, v2
	v_cvt_pk_bf16_f32 v154, v108, v109
	v_cvt_pk_bf16_f32 v155, v110, v111
	s_waitcnt lgkmcnt(12)
	v_mfma_f32_32x32x16_bf16 v[128:143], v[192:195], v[168:171], v[128:143]
	ds_read_b64_tr_b16 v[2:3], v0 offset:26624
	ds_read_b64_tr_b16 v[4:5], v0 offset:27136
	s_waitcnt lgkmcnt(13)
	v_mfma_f32_32x32x16_bf16 v[112:127], v[188:191], v[164:167], v[112:127]
	v_add_f32_e32 v14, v92, v14
	v_cvt_pk_bf16_f32 v148, v80, v81
	v_cvt_pk_bf16_f32 v149, v82, v83
	ds_read_b64_tr_b16 v[196:197], v0 offset:30720
	ds_read_b64_tr_b16 v[198:199], v0 offset:31232
	v_add_f32_e32 v14, v93, v14
	v_cvt_pk_bf16_f32 v150, v84, v85
	v_cvt_pk_bf16_f32 v151, v86, v87
	s_waitcnt lgkmcnt(14)
	v_mfma_f32_32x32x16_bf16 v[128:143], v[184:187], v[164:167], v[128:143]
	ds_read_b64_tr_b16 v[192:193], v0 offset:27648
	ds_read_b64_tr_b16 v[194:195], v0 offset:28160
	s_waitcnt lgkmcnt(14)
	v_mfma_f32_32x32x16_bf16 v[112:127], v[180:183], v[160:163], v[112:127]
	v_add_f32_e32 v14, v94, v14
	v_cvt_pk_bf16_f32 v144, v88, v89
	v_cvt_pk_bf16_f32 v145, v90, v91
	ds_read_b64_tr_b16 v[188:189], v0 offset:31744
	ds_read_b64_tr_b16 v[190:191], v0 offset:32256
	v_add_f32_e32 v96, v95, v14
	v_cvt_pk_bf16_f32 v146, v92, v93
	v_cvt_pk_bf16_f32 v147, v94, v95
	v_mfma_f32_32x32x16_bf16 v[128:143], v[176:179], v[160:163], v[128:143]
	s_nop 2
	v_add_f32_e64 v80, v112, -v228
	v_add_f32_e64 v81, v113, -v228
	s_nop 6
	v_sub_f32_e32 v14, v128, v228
	v_sub_f32_e32 v15, v129, v228
	v_sub_f32_e32 v98, v114, v228
	v_sub_f32_e32 v99, v115, v228
	v_sub_f32_e32 v82, v130, v228
	v_sub_f32_e32 v83, v131, v228
	v_max_f32_e32 v97, v80, v81
	v_sub_f32_e32 v100, v116, v228
	v_sub_f32_e32 v101, v117, v228
	v_sub_f32_e32 v102, v118, v228
	v_sub_f32_e32 v103, v119, v228
	v_max3_f32 v112, v98, v99, v15
	v_max3_f32 v97, v97, v14, v82
	s_add_u32 s30, s16, s10
	v_sub_f32_e32 v84, v132, v228
	v_sub_f32_e32 v85, v133, v228
	v_sub_f32_e32 v86, v134, v228
	v_sub_f32_e32 v87, v135, v228
	v_max3_f32 v97, v97, v83, v100
	v_max3_f32 v112, v112, v102, v103
	s_addc_u32 s31, s17, s11
	v_sub_f32_e32 v104, v120, v228
	v_sub_f32_e32 v105, v121, v228
	v_sub_f32_e32 v106, v122, v228
	v_sub_f32_e32 v107, v123, v228
	v_max3_f32 v97, v97, v101, v84
	v_max3_f32 v112, v112, v86, v87
	s_add_u32 s22, s30, 0x80000
	v_sub_f32_e32 v88, v136, v228
	v_sub_f32_e32 v89, v137, v228
	v_sub_f32_e32 v90, v138, v228
	v_sub_f32_e32 v91, v139, v228
	v_max3_f32 v97, v97, v85, v104
	v_max3_f32 v112, v112, v106, v107
	s_addc_u32 s23, s31, 0
	s_add_i32 s24, s29, s57
	v_sub_f32_e32 v108, v124, v228
	v_sub_f32_e32 v109, v125, v228
	v_sub_f32_e32 v110, v126, v228
	v_sub_f32_e32 v111, v127, v228
	v_max3_f32 v97, v97, v105, v88
	v_max3_f32 v112, v112, v90, v91
	s_add_u32 s62, s18, s10
	v_sub_f32_e32 v92, v140, v228
	v_sub_f32_e32 v93, v141, v228
	v_sub_f32_e32 v94, v142, v228
	v_sub_f32_e32 v95, v143, v228
	v_max3_f32 v97, v97, v89, v108
	v_max3_f32 v112, v112, v110, v111
	s_addc_u32 s63, s19, s11
	v_max3_f32 v97, v97, v109, v92
	v_max3_f32 v112, v112, v94, v95
	s_mov_b32 s25, m0
	s_mov_b32 m0, s24
	s_nop 0
	global_load_lds_dwordx4 v241, s[22:23]
	s_mov_b32 m0, s25
	s_add_u32 s22, s62, 0x40000
	v_add_f32_e32 v116, v224, v96
	v_max3_f32 v96, v97, v93, v112
	s_addc_u32 s23, s63, 0
	s_add_i32 s24, s28, s58
	v_mov_b32_e32 v97, v96
	s_add_u32 s64, s20, s10
	s_nop 0
	v_permlane32_swap_b32_e32 v96, v97
	s_addc_u32 s65, s21, s11
	v_max_f32_e32 v97, v97, v97
	v_max_f32_e32 v96, v96, v96
	s_mov_b32 s25, m0
	s_mov_b32 m0, s24
	s_nop 0
	global_load_lds_dwordx4 v242, s[22:23]
	s_mov_b32 m0, s25
	s_add_u32 s22, s64, 0x40000
	v_max_f32_e32 v96, v96, v97
	s_addc_u32 s23, s65, 0
	s_add_i32 s24, s28, s59
	s_mov_b32 s25, m0
	s_mov_b32 m0, s24
	s_nop 0
	global_load_lds_dwordx4 v242, s[22:23]
	s_mov_b32 m0, s25
	v_cmp_lt_f32_e32 vcc, s35, v96
	s_cmp_lg_u64 vcc, 0
	s_cselect_b64 s[22:23], -1, 0
	s_cbranch_vccnz .LBB0_1612

.LBB0_1607:
	s_add_i32 s22, s28, 0x2000
	s_cmpk_lg_i32 s28, 0x4000
	s_cselect_b32 s61, s22, 0
	v_add_f32_e32 v15, v116, v14
	v_add_u32_e32 v14, s29, v244
	ds_read_b64_tr_b16 v[196:197], v14 offset:24576
	ds_read_b64_tr_b16 v[198:199], v14 offset:25088
	v_add_f32_e32 v132, v87, v88
	v_cvt_pk_bf16_f32 v156, v96, v97
	v_cvt_pk_bf16_f32 v157, v98, v99
	v_mfma_f32_32x32x16_bf16 v[112:127], v[112:115], v[172:175], 0
	ds_read_b64_tr_b16 v[192:193], v14 offset:28672
	ds_read_b64_tr_b16 v[194:195], v14 offset:29184
	v_add_f32_e32 v96, v89, v132
	v_cvt_pk_bf16_f32 v158, v100, v101
	v_cvt_pk_bf16_f32 v159, v102, v103
	v_mfma_f32_32x32x16_bf16 v[128:143], v[128:131], v[172:175], 0
	ds_read_b64_tr_b16 v[188:189], v14 offset:25600
	ds_read_b64_tr_b16 v[190:191], v14 offset:26112
	v_add_f32_e32 v96, v90, v96
	v_cvt_pk_bf16_f32 v152, v104, v105
	v_cvt_pk_bf16_f32 v153, v106, v107
	v_mfma_f32_32x32x16_bf16 v[112:127], v[184:187], v[168:171], v[112:127]
	ds_read_b64_tr_b16 v[184:185], v14 offset:29696
	ds_read_b64_tr_b16 v[186:187], v14 offset:30208
	v_add_f32_e32 v96, v91, v96
	v_cvt_pk_bf16_f32 v154, v108, v109
	v_cvt_pk_bf16_f32 v155, v110, v111
	v_mfma_f32_32x32x16_bf16 v[128:143], v[176:179], v[168:171], v[128:143]
	ds_read_b64_tr_b16 v[176:177], v14 offset:26624
	ds_read_b64_tr_b16 v[178:179], v14 offset:27136
	v_add_f32_e32 v96, v92, v96
	v_cvt_pk_bf16_f32 v148, v80, v81
	v_cvt_pk_bf16_f32 v149, v82, v83
	v_mfma_f32_32x32x16_bf16 v[112:127], v[180:183], v[164:167], v[112:127]
	ds_read_b64_tr_b16 v[212:213], v14 offset:30720
	ds_read_b64_tr_b16 v[214:215], v14 offset:31232
	v_add_f32_e32 v80, v93, v96
	v_cvt_pk_bf16_f32 v150, v84, v85
	v_cvt_pk_bf16_f32 v151, v86, v87
	v_mfma_f32_32x32x16_bf16 v[128:143], v[6:9], v[164:167], v[128:143]
	ds_read_b64_tr_b16 v[208:209], v14 offset:27648
	ds_read_b64_tr_b16 v[210:211], v14 offset:28160
	v_add_f32_e32 v80, v94, v80
	v_cvt_pk_bf16_f32 v144, v88, v89
	v_cvt_pk_bf16_f32 v145, v90, v91
	v_mfma_f32_32x32x16_bf16 v[112:127], v[10:13], v[160:163], v[112:127]
	ds_read_b64_tr_b16 v[6:7], v14 offset:31744
	ds_read_b64_tr_b16 v[8:9], v14 offset:32256
	v_add_f32_e32 v10, v95, v80
	v_cvt_pk_bf16_f32 v146, v92, v93
	v_cvt_pk_bf16_f32 v147, v94, v95
	v_mfma_f32_32x32x16_bf16 v[128:143], v[2:5], v[160:163], v[128:143]
	s_nop 5
	v_add_f32_e64 v4, v112, -v228
	v_add_f32_e64 v5, v113, -v228
	s_nop 3
	v_sub_f32_e32 v2, v128, v228
	v_sub_f32_e32 v3, v129, v228
	v_sub_f32_e32 v98, v114, v228
	v_sub_f32_e32 v99, v115, v228
	v_sub_f32_e32 v82, v130, v228
	v_sub_f32_e32 v83, v131, v228
	v_max_f32_e32 v11, v4, v5
	v_sub_f32_e32 v100, v116, v228
	v_sub_f32_e32 v101, v117, v228
	v_sub_f32_e32 v102, v118, v228
	v_sub_f32_e32 v103, v119, v228
	v_max3_f32 v12, v98, v99, v3
	v_max3_f32 v11, v11, v2, v82
	v_sub_f32_e32 v84, v132, v228
	v_sub_f32_e32 v85, v133, v228
	v_sub_f32_e32 v86, v134, v228
	v_sub_f32_e32 v87, v135, v228
	v_max3_f32 v11, v11, v83, v100
	v_max3_f32 v12, v12, v102, v103
	v_sub_f32_e32 v104, v120, v228
	v_sub_f32_e32 v105, v121, v228
	v_sub_f32_e32 v106, v122, v228
	v_sub_f32_e32 v107, v123, v228
	v_max3_f32 v11, v11, v101, v84
	v_max3_f32 v12, v12, v86, v87
	v_sub_f32_e32 v88, v136, v228
	v_sub_f32_e32 v89, v137, v228
	v_sub_f32_e32 v90, v138, v228
	v_sub_f32_e32 v91, v139, v228
	v_max3_f32 v11, v11, v85, v104
	v_max3_f32 v12, v12, v106, v107
	v_sub_f32_e32 v108, v124, v228
	v_sub_f32_e32 v109, v125, v228
	v_sub_f32_e32 v110, v126, v228
	v_sub_f32_e32 v111, v127, v228
	v_max3_f32 v11, v11, v105, v88
	v_max3_f32 v12, v12, v90, v91
	v_sub_f32_e32 v92, v140, v228
	v_sub_f32_e32 v93, v141, v228
	v_sub_f32_e32 v94, v142, v228
	v_sub_f32_e32 v95, v143, v228
	v_max3_f32 v11, v11, v89, v108
	v_max3_f32 v12, v12, v110, v111
	v_max3_f32 v11, v11, v109, v92
	v_max3_f32 v12, v12, v94, v95
	s_add_u32 s22, s30, 0xa0000
	v_max3_f32 v11, v11, v93, v12
	s_addc_u32 s23, s31, 0
	s_add_i32 s24, s28, s57
	v_mov_b32_e32 v12, v11
	s_mov_b32 s25, m0
	s_mov_b32 m0, s24
	s_nop 0
	global_load_lds_dwordx4 v241, s[22:23]
	s_mov_b32 m0, s25
	s_add_u32 s22, s62, 0x60000
	s_nop 0
	v_permlane32_swap_b32_e32 v11, v12
	s_addc_u32 s23, s63, 0
	s_add_i32 s24, s61, s58
	v_max_f32_e32 v12, v12, v12
	v_max_f32_e32 v11, v11, v11
	s_mov_b32 s25, m0
	s_mov_b32 m0, s24
	s_nop 0
	global_load_lds_dwordx4 v242, s[22:23]
	s_mov_b32 m0, s25
	s_add_u32 s22, s64, 0x60000
	v_max_f32_e32 v11, v11, v12
	s_addc_u32 s23, s65, 0
	s_add_i32 s24, s61, s59
	s_mov_b32 s25, m0
	s_mov_b32 m0, s24
	s_nop 0
	global_load_lds_dwordx4 v242, s[22:23]
	s_mov_b32 m0, s25
	v_cmp_lt_f32_e32 vcc, s35, v11
	s_cmp_lg_u64 vcc, 0
	v_add_f32_e32 v10, v15, v10
	s_cselect_b64 s[22:23], -1, 0
	s_cbranch_vccnz .LBB0_1615

.LBB0_1620:
	v_add_u32_e32 v212, s62, v244
	ds_read_b64_tr_b16 v[208:209], v212 offset:24576
	ds_read_b64_tr_b16 v[210:211], v212 offset:25088
	v_add_f32_e32 v0, v87, v88
	v_cvt_pk_bf16_f32 v156, v96, v97
	v_cvt_pk_bf16_f32 v157, v98, v99
	s_waitcnt lgkmcnt(9)
	v_mfma_f32_32x32x16_bf16 v[112:127], v[204:207], v[172:175], 0
	ds_read_b64_tr_b16 v[204:205], v212 offset:28672
	ds_read_b64_tr_b16 v[206:207], v212 offset:29184
	v_add_f32_e32 v0, v89, v0
	v_cvt_pk_bf16_f32 v158, v100, v101
	v_cvt_pk_bf16_f32 v159, v102, v103
	s_waitcnt lgkmcnt(10)
	v_mfma_f32_32x32x16_bf16 v[128:143], v[200:203], v[172:175], 0
	ds_read_b64_tr_b16 v[200:201], v212 offset:25600
	ds_read_b64_tr_b16 v[202:203], v212 offset:26112
	v_add_f32_e32 v0, v90, v0
	v_cvt_pk_bf16_f32 v152, v104, v105
	v_cvt_pk_bf16_f32 v153, v106, v107
	s_waitcnt lgkmcnt(11)
	v_mfma_f32_32x32x16_bf16 v[112:127], v[196:199], v[168:171], v[112:127]
	ds_read_b64_tr_b16 v[172:173], v212 offset:29696
	ds_read_b64_tr_b16 v[174:175], v212 offset:30208
	v_add_f32_e32 v0, v91, v0
	v_cvt_pk_bf16_f32 v154, v108, v109
	v_cvt_pk_bf16_f32 v155, v110, v111
	s_waitcnt lgkmcnt(12)
	v_mfma_f32_32x32x16_bf16 v[128:143], v[192:195], v[168:171], v[128:143]
	ds_read_b64_tr_b16 v[168:169], v212 offset:26624
	ds_read_b64_tr_b16 v[170:171], v212 offset:27136
	v_add_f32_e32 v0, v92, v0
	v_cvt_pk_bf16_f32 v148, v80, v81
	v_cvt_pk_bf16_f32 v149, v82, v83
	s_waitcnt lgkmcnt(13)
	v_mfma_f32_32x32x16_bf16 v[112:127], v[188:191], v[164:167], v[112:127]
	ds_read_b64_tr_b16 v[10:11], v212 offset:30720
	ds_read_b64_tr_b16 v[12:13], v212 offset:31232
	v_add_f32_e32 v0, v93, v0
	v_cvt_pk_bf16_f32 v150, v84, v85
	v_cvt_pk_bf16_f32 v151, v86, v87
	s_waitcnt lgkmcnt(14)
	v_mfma_f32_32x32x16_bf16 v[128:143], v[184:187], v[164:167], v[128:143]
	ds_read_b64_tr_b16 v[6:7], v212 offset:27648
	ds_read_b64_tr_b16 v[8:9], v212 offset:28160
	v_add_f32_e32 v0, v94, v0
	v_cvt_pk_bf16_f32 v144, v88, v89
	v_cvt_pk_bf16_f32 v145, v90, v91
	s_waitcnt lgkmcnt(14)
	v_mfma_f32_32x32x16_bf16 v[112:127], v[180:183], v[160:163], v[112:127]
	ds_read_b64_tr_b16 v[2:3], v212 offset:31744
	ds_read_b64_tr_b16 v[4:5], v212 offset:32256
	v_add_f32_e32 v0, v95, v0
	v_cvt_pk_bf16_f32 v146, v92, v93
	v_cvt_pk_bf16_f32 v147, v94, v95
	v_mfma_f32_32x32x16_bf16 v[128:143], v[176:179], v[160:163], v[128:143]
	v_or_b32_e32 v14, 0xe0, v239
	v_or_b32_e32 v15, 0xc0, v239
	v_cmp_le_i32_e32 vcc, v14, v240
	v_or_b32_e32 v82, 0xc2, v239
	v_or_b32_e32 v83, 0xe2, v239
	s_nop 6
	v_cndmask_b32_e32 v14, v230, v128, vcc
	v_cmp_lt_i32_e32 vcc, v15, v240
	v_or_b32_e32 v85, 0xe3, v239
	v_or_b32_e32 v86, 0xc8, v239
	v_cndmask_b32_e32 v81, v230, v113, vcc
	v_cmp_le_i32_e32 vcc, v15, v240
	v_or_b32_e32 v15, 0xe1, v239
	v_or_b32_e32 v87, 0xe8, v239
	v_cndmask_b32_e32 v80, v230, v112, vcc
	v_cmp_le_i32_e32 vcc, v15, v240
	v_or_b32_e32 v89, 0xe9, v239
	v_or_b32_e32 v90, 0xca, v239
	v_cndmask_b32_e32 v15, v230, v129, vcc
	v_cmp_le_i32_e32 vcc, v82, v240
	v_or_b32_e32 v91, 0xea, v239
	v_or_b32_e32 v93, 0xeb, v239
	v_cndmask_b32_e32 v82, v230, v114, vcc
	v_cmp_le_i32_e32 vcc, v83, v240
	v_or_b32_e32 v83, 0xc3, v239
	v_or_b32_e32 v94, 0xd0, v239
	v_cndmask_b32_e32 v84, v230, v130, vcc
	v_cmp_le_i32_e32 vcc, v83, v240
	v_or_b32_e32 v95, 0xf0, v239
	v_or_b32_e32 v97, 0xf1, v239
	v_cndmask_b32_e32 v83, v230, v115, vcc
	v_cmp_le_i32_e32 vcc, v85, v240
	v_or_b32_e32 v98, 0xd2, v239
	v_sub_f32_e32 v80, v80, v228
	v_sub_f32_e32 v81, v81, v228
	v_cndmask_b32_e32 v85, v230, v131, vcc
	v_cmp_le_i32_e32 vcc, v86, v240
	v_sub_f32_e32 v14, v14, v228
	v_sub_f32_e32 v15, v15, v228
	v_add_f32_e32 v0, v224, v0
	v_cndmask_b32_e32 v86, v230, v116, vcc
	v_cmp_le_i32_e32 vcc, v87, v240
	v_or_b32_e32 v87, 0xc9, v239
	s_nop 0
	v_cndmask_b32_e32 v88, v230, v132, vcc
	v_cmp_le_i32_e32 vcc, v87, v240
	s_nop 1
	v_cndmask_b32_e32 v87, v230, v117, vcc
	v_cmp_le_i32_e32 vcc, v89, v240
	v_sub_f32_e32 v100, v86, v228
	v_sub_f32_e32 v101, v87, v228
	s_nop 0
	v_cndmask_b32_e32 v89, v230, v133, vcc
	v_cmp_le_i32_e32 vcc, v90, v240
	s_nop 1
	v_cndmask_b32_e32 v90, v230, v118, vcc
	v_cmp_le_i32_e32 vcc, v91, v240
	v_or_b32_e32 v91, 0xcb, v239
	s_nop 0
	v_cndmask_b32_e32 v92, v230, v134, vcc
	v_cmp_le_i32_e32 vcc, v91, v240
	s_nop 1
	v_cndmask_b32_e32 v91, v230, v119, vcc
	v_cmp_le_i32_e32 vcc, v93, v240
	v_sub_f32_e32 v102, v90, v228
	v_sub_f32_e32 v103, v91, v228
	s_nop 0
	v_cndmask_b32_e32 v93, v230, v135, vcc
	v_cmp_le_i32_e32 vcc, v94, v240
	v_sub_f32_e32 v86, v92, v228
	v_sub_f32_e32 v87, v93, v228
	s_nop 0
	v_cndmask_b32_e32 v94, v230, v120, vcc
	v_cmp_le_i32_e32 vcc, v95, v240
	v_or_b32_e32 v95, 0xd1, v239
	s_nop 0
	v_cndmask_b32_e32 v96, v230, v136, vcc
	v_cmp_le_i32_e32 vcc, v95, v240
	s_nop 1
	v_cndmask_b32_e32 v95, v230, v121, vcc
	v_cmp_le_i32_e32 vcc, v97, v240
	v_sub_f32_e32 v104, v94, v228
	v_sub_f32_e32 v105, v95, v228
	s_nop 0
	v_cndmask_b32_e32 v97, v230, v137, vcc
	v_cmp_le_i32_e32 vcc, v98, v240
	v_or_b32_e32 v98, 0xf2, v239
	s_nop 0
	v_cndmask_b32_e32 v106, v230, v122, vcc
	v_cmp_le_i32_e32 vcc, v98, v240
	v_or_b32_e32 v98, 0xd3, v239
	s_nop 0
	v_cndmask_b32_e32 v108, v230, v138, vcc
	v_cmp_le_i32_e32 vcc, v98, v240
	v_or_b32_e32 v98, 0xf3, v239
	s_nop 0
	v_cndmask_b32_e32 v107, v230, v123, vcc
	v_cmp_le_i32_e32 vcc, v98, v240
	v_or_b32_e32 v98, 0xd8, v239
	v_sub_f32_e32 v106, v106, v228
	v_sub_f32_e32 v107, v107, v228
	v_cndmask_b32_e32 v109, v230, v139, vcc
	v_cmp_le_i32_e32 vcc, v98, v240
	v_or_b32_e32 v98, 0xf8, v239
	v_sub_f32_e32 v90, v108, v228
	v_sub_f32_e32 v91, v109, v228
	v_cndmask_b32_e32 v110, v230, v124, vcc
	v_cmp_le_i32_e32 vcc, v98, v240
	v_or_b32_e32 v98, 0xd9, v239
	s_nop 0
	v_cndmask_b32_e32 v112, v230, v140, vcc
	v_cmp_le_i32_e32 vcc, v98, v240
	v_or_b32_e32 v98, 0xf9, v239
	s_nop 0
	v_cndmask_b32_e32 v111, v230, v125, vcc
	v_cmp_le_i32_e32 vcc, v98, v240
	v_or_b32_e32 v98, 0xda, v239
	v_sub_f32_e32 v108, v110, v228
	v_sub_f32_e32 v109, v111, v228
	v_cndmask_b32_e32 v113, v230, v141, vcc
	v_cmp_le_i32_e32 vcc, v98, v240
	v_or_b32_e32 v98, 0xfa, v239
	v_sub_f32_e32 v92, v112, v228
	v_sub_f32_e32 v93, v113, v228
	v_cndmask_b32_e32 v114, v230, v126, vcc
	v_cmp_le_i32_e32 vcc, v98, v240
	v_or_b32_e32 v98, 0xdb, v239
	s_nop 0
	v_cndmask_b32_e32 v116, v230, v142, vcc
	v_cmp_le_i32_e32 vcc, v98, v240
	v_or_b32_e32 v98, 0xfb, v239
	s_nop 0
	v_cndmask_b32_e32 v115, v230, v127, vcc
	v_cmp_le_i32_e32 vcc, v98, v240
	v_sub_f32_e32 v98, v82, v228
	v_sub_f32_e32 v99, v83, v228
	v_sub_f32_e32 v82, v84, v228
	v_sub_f32_e32 v83, v85, v228
	v_sub_f32_e32 v84, v88, v228
	v_sub_f32_e32 v85, v89, v228
	v_sub_f32_e32 v88, v96, v228
	v_sub_f32_e32 v89, v97, v228
	v_max_f32_e32 v96, v80, v81
	v_max3_f32 v97, v98, v99, v15
	v_max3_f32 v96, v96, v14, v82
	v_max3_f32 v96, v96, v83, v100
	v_max3_f32 v97, v97, v102, v103
	v_max3_f32 v96, v96, v101, v84
	v_max3_f32 v97, v97, v86, v87
	v_max3_f32 v96, v96, v85, v104
	v_max3_f32 v97, v97, v106, v107
	v_cndmask_b32_e32 v117, v230, v143, vcc
	v_sub_f32_e32 v110, v114, v228
	v_sub_f32_e32 v111, v115, v228
	v_max3_f32 v96, v96, v105, v88
	v_max3_f32 v97, v97, v90, v91
	v_sub_f32_e32 v94, v116, v228
	v_sub_f32_e32 v95, v117, v228
	v_max3_f32 v96, v96, v89, v108
	v_max3_f32 v97, v97, v110, v111
	v_max3_f32 v96, v96, v109, v92
	v_max3_f32 v97, v97, v94, v95
	v_max3_f32 v96, v96, v93, v97
	v_mov_b32_e32 v97, v96
	s_nop 1
	v_permlane32_swap_b32_e32 v96, v97
	v_max_f32_e32 v97, v97, v97
	v_max_f32_e32 v96, v96, v96
	v_max_f32_e32 v96, v96, v97
	v_cmp_lt_f32_e32 vcc, s35, v96
	s_cmp_lg_u64 vcc, 0
	s_cselect_b64 s[8:9], -1, 0
	s_cbranch_vccnz .LBB0_1675

.LBB0_1631:
	v_sub_f32_e32 v80, v112, v228
	v_sub_f32_e32 v81, v113, v228
	v_add_f32_e32 v247, v224, v14
	v_sub_f32_e32 v14, v128, v228
	v_sub_f32_e32 v15, v129, v228
	v_sub_f32_e32 v98, v114, v228
	v_sub_f32_e32 v99, v115, v228
	v_sub_f32_e32 v82, v130, v228
	v_sub_f32_e32 v83, v131, v228
	v_max_f32_e32 v96, v80, v81
	v_sub_f32_e32 v100, v116, v228
	v_sub_f32_e32 v101, v117, v228
	v_sub_f32_e32 v102, v118, v228
	v_sub_f32_e32 v103, v119, v228
	v_max3_f32 v97, v98, v99, v15
	v_max3_f32 v96, v96, v14, v82
	v_sub_f32_e32 v84, v132, v228
	v_sub_f32_e32 v85, v133, v228
	v_sub_f32_e32 v86, v134, v228
	v_sub_f32_e32 v87, v135, v228
	v_max3_f32 v96, v96, v83, v100
	v_max3_f32 v97, v97, v102, v103
	v_sub_f32_e32 v104, v120, v228
	v_sub_f32_e32 v105, v121, v228
	v_sub_f32_e32 v106, v122, v228
	v_sub_f32_e32 v107, v123, v228
	v_max3_f32 v96, v96, v101, v84
	v_max3_f32 v97, v97, v86, v87
	v_sub_f32_e32 v88, v136, v228
	v_sub_f32_e32 v89, v137, v228
	v_sub_f32_e32 v90, v138, v228
	v_sub_f32_e32 v91, v139, v228
	v_max3_f32 v96, v96, v85, v104
	v_max3_f32 v97, v97, v106, v107
	v_sub_f32_e32 v108, v124, v228
	v_sub_f32_e32 v109, v125, v228
	v_sub_f32_e32 v110, v126, v228
	v_sub_f32_e32 v111, v127, v228
	v_max3_f32 v96, v96, v105, v88
	v_max3_f32 v97, v97, v90, v91
	v_sub_f32_e32 v92, v140, v228
	v_sub_f32_e32 v93, v141, v228
	v_sub_f32_e32 v94, v142, v228
	v_sub_f32_e32 v95, v143, v228
	v_max3_f32 v96, v96, v89, v108
	v_max3_f32 v97, v97, v110, v111
	v_max3_f32 v96, v96, v109, v92
	v_max3_f32 v97, v97, v94, v95
	v_max3_f32 v96, v96, v93, v97
	v_mov_b32_e32 v97, v96
	s_nop 1
	v_permlane32_swap_b32_e32 v96, v97
	v_max_f32_e32 v97, v97, v97
	v_max_f32_e32 v96, v96, v96
	v_max_f32_e32 v96, v96, v97
	v_cmp_lt_f32_e32 vcc, s35, v96
	s_cmp_lg_u64 vcc, 0
	s_cselect_b64 s[10:11], -1, 0
	s_cbranch_vccnz .LBB0_1669

.LBB0_1642:
	v_add_f32_e32 v14, v247, v14
	v_sub_f32_e32 v80, v112, v228
	v_sub_f32_e32 v81, v113, v228
	v_add_f32_e32 v247, v14, v15
	v_sub_f32_e32 v14, v128, v228
	v_sub_f32_e32 v15, v129, v228
	v_sub_f32_e32 v98, v114, v228
	v_sub_f32_e32 v99, v115, v228
	v_sub_f32_e32 v82, v130, v228
	v_sub_f32_e32 v83, v131, v228
	v_max_f32_e32 v96, v80, v81
	v_sub_f32_e32 v100, v116, v228
	v_sub_f32_e32 v101, v117, v228
	v_sub_f32_e32 v102, v118, v228
	v_sub_f32_e32 v103, v119, v228
	v_max3_f32 v97, v98, v99, v15
	v_max3_f32 v96, v96, v14, v82
	v_sub_f32_e32 v84, v132, v228
	v_sub_f32_e32 v85, v133, v228
	v_sub_f32_e32 v86, v134, v228
	v_sub_f32_e32 v87, v135, v228
	v_max3_f32 v96, v96, v83, v100
	v_max3_f32 v97, v97, v102, v103
	v_sub_f32_e32 v104, v120, v228
	v_sub_f32_e32 v105, v121, v228
	v_sub_f32_e32 v106, v122, v228
	v_sub_f32_e32 v107, v123, v228
	v_max3_f32 v96, v96, v101, v84
	v_max3_f32 v97, v97, v86, v87
	v_sub_f32_e32 v88, v136, v228
	v_sub_f32_e32 v89, v137, v228
	v_sub_f32_e32 v90, v138, v228
	v_sub_f32_e32 v91, v139, v228
	v_max3_f32 v96, v96, v85, v104
	v_max3_f32 v97, v97, v106, v107
	v_sub_f32_e32 v108, v124, v228
	v_sub_f32_e32 v109, v125, v228
	v_sub_f32_e32 v110, v126, v228
	v_sub_f32_e32 v111, v127, v228
	v_max3_f32 v96, v96, v105, v88
	v_max3_f32 v97, v97, v90, v91
	v_sub_f32_e32 v92, v140, v228
	v_sub_f32_e32 v93, v141, v228
	v_sub_f32_e32 v94, v142, v228
	v_sub_f32_e32 v95, v143, v228
	v_max3_f32 v96, v96, v89, v108
	v_max3_f32 v97, v97, v110, v111
	v_max3_f32 v96, v96, v109, v92
	v_max3_f32 v97, v97, v94, v95
	v_max3_f32 v96, v96, v93, v97
	v_mov_b32_e32 v97, v96
	s_nop 1
	v_permlane32_swap_b32_e32 v96, v97
	v_max_f32_e32 v97, v97, v97
	v_max_f32_e32 v96, v96, v96
	v_max_f32_e32 v96, v96, v97
	v_cmp_lt_f32_e32 vcc, s35, v96
	s_cmp_lg_u64 vcc, 0
	s_cselect_b64 s[28:29], -1, 0
	s_cbranch_vccnz .LBB0_1672
